# A0 tile loop: deferred PV MFMAs issued first at the loop head (before the per-tile activity test), loop bookkeeping moved before the closing barrier
# baseline (speedup 1.0000x reference)
; template <int DQK, int NHQ, int NHKV, bool HAS_META>
; DI void attn_phase(const u16* __restrict__ Q, const u16* __restrict__ K, const u16* __restrict__ Vt, u16* __restrict__ O, const float* __restrict__ qg, const float* __restrict__ kg, char* smem, const int wv) {
;     ...
;     for (int j = 0; j < NT; ++j) {
;       __builtin_amdgcn_s_setprio(0);
;       if (active) {
;     ...
;         for (int i = 0; i < NM; ++i) {
;           if (i < NQK) {
;             if (i & 1) s1 = __builtin_amdgcn_mfma_f32_32x32x16_bf16(ring[i % RING], qf[i >> 1], s1, 0, 0, 0);
;             else       s0 = __builtin_amdgcn_mfma_f32_32x32x16_bf16(ring[i % RING], qf[i >> 1], s0, 0, 0, 0);
;           } else {
;             o[(i - NQK) & 3] = __builtin_amdgcn_mfma_f32_32x32x16_bf16(ring[i % RING], pb[(i - NQK) >> 2], o[(i - NQK) & 3], 0, 0, 0);
;           }
.LBB0_676:
	s_cmp_eq_u32 s59, 0
	s_cbranch_scc1 .Lmy_a0_nodef_loop
	v_mfma_f32_32x32x16_bf16 v[96:111], v[238:241], v[132:135], v[96:111]
	v_mfma_f32_32x32x16_bf16 v[80:95], v[242:245], v[132:135], v[80:95]
	v_mfma_f32_32x32x16_bf16 v[64:79], v[246:249], v[132:135], v[64:79]
	v_mfma_f32_32x32x16_bf16 v[48:63], v[250:253], v[132:135], v[48:63]
	v_mfma_f32_32x32x16_bf16 v[96:111], v[226:229], v[136:139], v[96:111]
	v_mfma_f32_32x32x16_bf16 v[80:95], v[222:225], v[136:139], v[80:95]
	v_mfma_f32_32x32x16_bf16 v[64:79], v[10:13], v[136:139], v[64:79]
	v_mfma_f32_32x32x16_bf16 v[48:63], v[6:9], v[136:139], v[48:63]

; DI unsigned cvtpk(float lo, float hi) { f32x2 v = {lo, hi}; return __builtin_bit_cast(unsigned, __builtin_convertvector(v, bf16x2_t)); }
; #define RAW_BAR() do { asm volatile("s_waitcnt lgkmcnt(0)" ::: "memory"); __builtin_amdgcn_s_barrier(); asm volatile("" ::: "memory"); } while (0)
; #define A_FETCH(j_) do { \
;         if ((j_) + 3 < NT) A_LOADK(Kb, (j_) + 3); \
;         else if ((j_) == NT - 3 && has_next) A_LOADK(nKb, 0); \
;         else if ((j_) == NT - 1 && has_next) A_LOADK(nKb, 1); \
;         if ((j_) + 2 < NT) A_LOADV(Vb, (j_) + 2); \
;         else if ((j_) == NT - 2 && has_next) A_LOADV(nVb, 0); } while (0)
; template <int DQK, int NHQ, int NHKV, bool HAS_META>
; DI void attn_phase(const u16* __restrict__ Q, const u16* __restrict__ K, const u16* __restrict__ Vt, u16* __restrict__ O, const float* __restrict__ qg, const float* __restrict__ kg, char* smem, const int wv) {
;     ...
;       if constexpr (!EARLY_FETCH) A_FETCH(j);
;       if (j == NT - 1 && valid) {
;         const float inv = 1.f / l;
;         u16* orow = O + (size_t)(HAS_META ? sq * L + pq : sq * SEQ + pq - NMETA) * DM + hq * 128 + hh * 4;
; #pragma unroll
;         for (int d = 0; d < 4; ++d)
; #pragma unroll
;           for (int q = 0; q < 4; ++q) {
;             u32x2 w = {cvtpk(o[d][4 * q] * inv, o[d][4 * q + 1] * inv), cvtpk(o[d][4 * q + 2] * inv, o[d][4 * q + 3] * inv)};
;             *(u32x2*)(orow + d * 32 + q * 8) = w;
;           }
;       }
;       RAW_BAR();
.LBB0_686:
	v_add_co_u32_e32 v2, vcc, 0xfff7e000, v210
	s_add_u32 s34, s34, 0x18000
	s_nop 0
	v_addc_co_u32_e32 v3, vcc, -1, v211, vcc
	global_load_dwordx4 v[140:143], v[2:3], off
	global_load_dwordx4 v[144:147], v[210:211], off
	s_addc_u32 s35, s35, 0
	s_cmp_eq_u32 s34, 0x5e8000
	v_lshl_add_u64 v[210:211], v[210:211], 0, s[22:23]
	s_waitcnt lgkmcnt(0)
	s_barrier
	s_cbranch_scc1 .LBB0_688
	s_mov_b32 s59, s61
	s_branch .LBB0_676
